# instruction selection: merged the 0+a row-sum adds and moved the rescale-factor select/compare ahead of the post-PV barrier in both attention loops (bit-identical)
# baseline (speedup 1.0000x reference)
; #define SBAR() __builtin_amdgcn_sched_barrier(0)
; #define SLOAD(i, k0) do { sr_[i].vs0 = *reinterpret_cast<const bf16x8*>(vptr + (size_t)((k0) + sr) * vstr); \
;     sr_[i].vs1 = *reinterpret_cast<const bf16x8*>(vptr + (size_t)((k0) + 32 + sr) * vstr); \
;     sr_[i].ks0 = *reinterpret_cast<const bf16x8*>(kptr + (size_t)((k0) + sr) * kstr); \
;     sr_[i].ks1 = *reinterpret_cast<const bf16x8*>(kptr + (size_t)((k0) + 32 + sr) * kstr); } while (0)
; __device__ __forceinline__ void partialSM(f32x16& p0, f32x16& p1, float& m_reg, float& mn, float& alpha, float C, float thr) {
;   float pmax = p0[0];
; #pragma unroll
;   for (int r = 1; r < 16; ++r) pmax = fmaxf(pmax, p0[r]);
; #pragma unroll
;   for (int r = 0; r < 16; ++r) pmax = fmaxf(pmax, p1[r]);
;   { auto rr = __builtin_amdgcn_permlane32_swap(__float_as_uint(pmax), __float_as_uint(pmax), false, false);
;     pmax = fmaxf(__uint_as_float(rr[0]), __uint_as_float(rr[1])); }
;   if (__builtin_expect(__all(pmax - m_reg <= thr), 1)) { mn = m_reg; alpha = 1.f; }
;   else { mn = fmaxf(m_reg, pmax); alpha = __builtin_amdgcn_exp2f((m_reg - mn) * C); m_reg = mn; }
;   const float mnC = -mn * C;
; #pragma unroll
;   for (int r = 0; r < 16; ++r) p0[r] = fmaf(p0[r], C, mnC);
; #pragma unroll
;   for (int r = 0; r < 16; ++r) p1[r] = fmaf(p1[r], C, mnC);
; #pragma unroll
;   for (int r = 0; r < 16; ++r) p0[r] = __builtin_amdgcn_exp2f(p0[r]);
; }
; __device__ __forceinline__ void finishSM(f32x16& p0, f32x16& p1, float alpha, float& l_reg, bf16x8& pa0, bf16x8& pa1, bf16x8& pa2, bf16x8& pa3) {
; #pragma unroll
;   for (int r = 0; r < 16; ++r) p1[r] = __builtin_amdgcn_exp2f(p1[r]);
; template <int NDQ, int NDV> ...
;     ...
;     SBAR(); qkt<NDQ>(pB0, pB1, K_lds + SHM_K, qr, r32, hi);
;     finishSM(pA0, pA1, alA, l_reg, pa0, pa1, pa2, pa3); SBAR();
;     SLOAD(SO, (j + 2) * 64); SBAR();
;     pv_d0<NDV>(o, vb0, pa0, pa1, pa2, pa3); partialSM(pB0, pB1, m_reg, mnB, alB, Cs, thr);
.LBB0_1488:
	ds_read_b128 v[32:35], v175 offset:49152
	ds_read_b128 v[36:39], v175 offset:57344
	ds_read_b128 v[192:195], v176 offset:49152
	ds_read_b128 v[196:199], v176 offset:57344
	ds_read_b128 v[200:203], v177 offset:49152
	ds_read_b128 v[204:207], v177 offset:57344
	ds_read_b128 v[208:211], v178 offset:49152
	ds_read_b128 v[212:215], v178 offset:57344
	ds_read_b128 v[216:219], v179 offset:49152
	ds_read_b128 v[220:223], v179 offset:57344
	v_add_f32_e32 v121, v130, v134
	s_waitcnt lgkmcnt(9)
	v_mfma_f32_32x32x16_bf16 v[48:63], v[32:35], v[84:87], 0
	v_add_f32_e32 v121, v131, v121
	v_add_f32_e32 v121, v135, v121
	v_add_f32_e32 v121, v132, v121
	v_add_f32_e32 v121, v185, v121
	v_add_f32_e32 v121, v133, v121
	v_add_f32_e32 v121, v186, v121
	v_add_f32_e32 v121, v122, v121
	v_add_f32_e32 v121, v125, v121
	s_waitcnt lgkmcnt(8)
	v_mfma_f32_32x32x16_bf16 v[32:47], v[36:39], v[84:87], 0
	v_add_f32_e32 v121, v123, v121
	v_add_f32_e32 v121, v126, v121
	v_exp_f32_e32 v116, v116
	v_add_f32_e32 v121, v124, v121
	v_exp_f32_e32 v117, v117
	v_add_f32_e32 v121, v127, v121
	s_waitcnt lgkmcnt(7)
	v_mfma_f32_32x32x16_bf16 v[48:63], v[192:195], v[80:83], v[48:63]
	v_exp_f32_e32 v114, v114
	v_add_f32_e32 v121, v128, v121
	v_exp_f32_e32 v115, v115
	v_add_f32_e32 v121, v129, v121
	v_exp_f32_e32 v110, v110
	s_waitcnt lgkmcnt(6)
	v_mfma_f32_32x32x16_bf16 v[32:47], v[196:199], v[80:83], v[32:47]
	v_add_f32_e32 v121, v116, v121
	v_exp_f32_e32 v111, v111
	v_add_f32_e32 v121, v117, v121
	v_exp_f32_e32 v106, v106
	v_add_f32_e32 v121, v114, v121
	s_waitcnt lgkmcnt(5)
	v_mfma_f32_32x32x16_bf16 v[48:63], v[200:203], v[76:79], v[48:63]
	ds_read_b128 v[224:227], v180 offset:49152
	ds_read_b128 v[228:231], v180 offset:57344
	v_exp_f32_e32 v107, v107
	v_add_f32_e32 v121, v115, v121
	v_exp_f32_e32 v104, v104
	v_add_f32_e32 v121, v110, v121
	v_exp_f32_e32 v105, v105
	s_waitcnt lgkmcnt(6)
	v_mfma_f32_32x32x16_bf16 v[32:47], v[204:207], v[76:79], v[32:47]
	v_add_f32_e32 v121, v111, v121
	v_exp_f32_e32 v118, v118
	v_add_f32_e32 v121, v106, v121
	v_exp_f32_e32 v119, v119
	v_add_f32_e32 v121, v107, v121
	s_waitcnt lgkmcnt(5)
	v_mfma_f32_32x32x16_bf16 v[48:63], v[208:211], v[72:75], v[48:63]
	v_exp_f32_e32 v112, v112
	v_add_f32_e32 v121, v104, v121
	v_exp_f32_e32 v113, v113
	v_add_f32_e32 v121, v105, v121
	v_exp_f32_e32 v108, v108
	s_waitcnt lgkmcnt(4)
	v_mfma_f32_32x32x16_bf16 v[32:47], v[212:215], v[72:75], v[32:47]
	v_add_f32_e32 v121, v118, v121
	v_exp_f32_e32 v109, v109
	v_add_f32_e32 v121, v119, v121
	v_add_f32_e32 v121, v112, v121
	v_add_f32_e32 v121, v113, v121
	v_add_f32_e32 v121, v108, v121
	v_add_f32_e32 v182, v109, v121
	s_waitcnt lgkmcnt(3)
	v_mfma_f32_32x32x16_bf16 v[48:63], v[216:219], v[68:71], v[48:63]
	v_mov_b32_e32 v183, v182
	v_cvt_pk_bf16_f32 v130, v130, v134
	v_cvt_pk_bf16_f32 v131, v131, v135
	v_cvt_pk_bf16_f32 v132, v132, v185
	v_cvt_pk_bf16_f32 v133, v133, v186
	v_cvt_pk_bf16_f32 v122, v122, v125
	v_cvt_pk_bf16_f32 v123, v123, v126
	v_cvt_pk_bf16_f32 v124, v124, v127
	s_waitcnt lgkmcnt(2)
	v_mfma_f32_32x32x16_bf16 v[32:47], v[220:223], v[68:71], v[32:47]
	v_cvt_pk_bf16_f32 v125, v128, v129
	v_cvt_pk_bf16_f32 v126, v116, v117
	v_cvt_pk_bf16_f32 v127, v114, v115
	v_cvt_pk_bf16_f32 v128, v110, v111
	v_cvt_pk_bf16_f32 v129, v106, v107
	v_cvt_pk_bf16_f32 v184, v104, v105
	v_cvt_pk_bf16_f32 v185, v118, v119
	v_cvt_pk_bf16_f32 v186, v112, v113
	s_waitcnt lgkmcnt(1)
	v_mfma_f32_32x32x16_bf16 v[48:63], v[224:227], v[64:67], v[48:63]
	v_permlane32_swap_b32_e32 v182, v183
	v_cvt_pk_bf16_f32 v187, v108, v109
	v_permlane32_swap_b32_e32 v184, v186
	v_permlane32_swap_b32_e32 v130, v132
	v_permlane32_swap_b32_e32 v131, v133
	v_permlane32_swap_b32_e32 v122, v124
	v_permlane32_swap_b32_e32 v123, v125
	v_permlane32_swap_b32_e32 v126, v128
	s_waitcnt lgkmcnt(0)
	v_mfma_f32_32x32x16_bf16 v[32:47], v[228:231], v[64:67], v[32:47]
	v_permlane32_swap_b32_e32 v127, v129
	v_permlane32_swap_b32_e32 v185, v187
	v_add_co_u32_e32 v104, vcc, s48, v154
	v_lshl_add_u64 v[112:113], v[150:151], 0, v[160:161]
	s_nop 0
	v_addc_co_u32_e32 v105, vcc, -1, v155, vcc
	v_add_co_u32_e32 v108, vcc, s49, v154
	v_lshl_add_u64 v[116:117], v[150:151], 0, v[158:159]
	s_nop 0
	v_addc_co_u32_e32 v109, vcc, -1, v155, vcc
	global_load_dwordx4 v[104:107], v[104:105], off
	s_nop 0
	global_load_dwordx4 v[108:111], v[108:109], off
	s_nop 0
	global_load_dwordx4 v[112:115], v[112:113], off
	s_nop 0
	global_load_dwordx4 v[116:119], v[116:117], off
	s_waitcnt vmcnt(4)
	ds_write_b128 v171, v[88:91] offset:32768
	ds_write_b128 v172, v[92:95] offset:32768
	ds_read_b64_tr_b16 v[192:193], v170 offset:0
	ds_read_b64_tr_b16 v[194:195], v170 offset:0x800
	ds_read_b64_tr_b16 v[196:197], v170 offset:0x1000
	ds_read_b64_tr_b16 v[198:199], v170 offset:0x1800
	ds_read_b64_tr_b16 v[200:201], v170 offset:0x2000
	ds_read_b64_tr_b16 v[202:203], v170 offset:0x2800
	ds_read_b64_tr_b16 v[204:205], v170 offset:0x3000
	ds_read_b64_tr_b16 v[206:207], v170 offset:0x3800
	s_waitcnt lgkmcnt(6)
	v_mfma_f32_32x32x16_bf16 v[0:15], v[130:133], v[192:195], v[0:15]
	ds_read_b64_tr_b16 v[192:193], v170 offset:0x200
	ds_read_b64_tr_b16 v[194:195], v170 offset:0xa00
	v_max_f32_e32 v121, v48, v49
	v_max3_f32 v121, v121, v50, v51
	v_max3_f32 v121, v121, v52, v53
	v_max3_f32 v121, v121, v54, v55
	v_max3_f32 v121, v121, v56, v57
	v_max3_f32 v121, v121, v58, v59
	v_max3_f32 v121, v121, v60, v61
	v_max3_f32 v121, v121, v62, v63
	v_max3_f32 v121, v121, v32, v33
	v_max3_f32 v121, v121, v34, v35
	v_max3_f32 v121, v121, v36, v37
	v_max3_f32 v121, v121, v38, v39
	s_waitcnt lgkmcnt(6)
	v_mfma_f32_32x32x16_bf16 v[0:15], v[122:125], v[196:199], v[0:15]
	ds_read_b64_tr_b16 v[196:197], v170 offset:0x1200
	ds_read_b64_tr_b16 v[198:199], v170 offset:0x1a00
	v_max3_f32 v121, v121, v40, v41
	v_max3_f32 v121, v121, v42, v43
	v_max3_f32 v121, v121, v44, v45
	v_max3_f32 v121, v121, v46, v47
	v_mov_b32_e32 v134, v121
	s_nop 1
	v_permlane32_swap_b32_e32 v121, v134
	v_max_f32_e32 v121, v121, v134
	v_sub_f32_e32 v135, v121, v120
	v_max_f32_e32 v121, v120, v121
	v_cmp_ge_f32_e32 vcc, s46, v135
	s_cmp_eq_u64 vcc, exec
	s_waitcnt lgkmcnt(6)
	v_mfma_f32_32x32x16_bf16 v[0:15], v[126:129], v[200:203], v[0:15]
	ds_read_b64_tr_b16 v[200:201], v170 offset:0x2200
	ds_read_b64_tr_b16 v[202:203], v170 offset:0x2a00
	ds_read_b64_tr_b16 v[208:209], v170 offset:0x3200
	ds_read_b64_tr_b16 v[210:211], v170 offset:0x3a00
	s_cselect_b64 s[6:7], -1, 0
	s_cbranch_scc0 .Lmla_rareA
; #define SWRITE(b, i) do { *(LAS bf16x8*)(V_lds + (b) * SHM_V + vst0) = sr_[i].vs0;          \
;     *(LAS bf16x8*)(V_lds + (b) * SHM_V + vst1) = sr_[i].vs1; const int kc = sc * 2;               \
;     *(LAS bf16x8*)(K_lds + (b) * SHM_K + KSWZ(sr, kc)) = sr_[i].ks0;                       \
;     *(LAS bf16x8*)(K_lds + (b) * SHM_K + KSWZ(32 + sr, kc)) = sr_[i].ks1; } while (0)
; #define SWAIT() asm volatile("s_waitcnt vmcnt(4)" ::: "memory")
; #define RESC(a) do { if (__any((a) < 1.f)) { if (hi == 0) al_l[r32] = (a); asm volatile("s_waitcnt lgkmcnt(0)" ::: "memory"); \
;     _Pragma("unroll") for (int d = 0; d < NDV; ++d) _Pragma("unroll") for (int r = 0; r < 16; ++r) o[d][r] *= al_l[crow(r, hi)]; } } while (0)
; __device__ __forceinline__ void partialSM(f32x16& p0, f32x16& p1, float& m_reg, float& mn, float& alpha, float C, float thr) {
;     ...
;   if (__builtin_expect(__all(pmax - m_reg <= thr), 1)) { mn = m_reg; alpha = 1.f; }
;   else { mn = fmaxf(m_reg, pmax); alpha = __builtin_amdgcn_exp2f((m_reg - mn) * C); m_reg = mn; }
;   const float mnC = -mn * C;
; #pragma unroll
;   for (int r = 0; r < 16; ++r) p0[r] = fmaf(p0[r], C, mnC);
; #pragma unroll
;   for (int r = 0; r < 16; ++r) p1[r] = fmaf(p1[r], C, mnC);
; #pragma unroll
;   for (int r = 0; r < 16; ++r) p0[r] = __builtin_amdgcn_exp2f(p0[r]);
; template <int NDQ, int NDV> ...
;     ...
;     pv_d0<NDV>(o, vb0, pa0, pa1, pa2, pa3); partialSM(pB0, pB1, m_reg, mnB, alB, Cs, thr);
;     __syncthreads(); SWAIT(); SWRITE(0, SE);
;     RESC(alB); __syncthreads();
.Lmla_backA:
	v_cndmask_b32_e64 v253, v121, v120, s[6:7]
	v_mul_f32_e32 v251, 0xbe16c740, v253
	s_waitcnt lgkmcnt(8)
	v_mfma_f32_32x32x16_bf16 v[0:15], v[184:187], v[204:207], v[0:15]
	v_fmamk_f32 v48, v48, 0x3e16c740, v251
	v_fmamk_f32 v49, v49, 0x3e16c740, v251
	v_fmamk_f32 v50, v50, 0x3e16c740, v251
	v_fmamk_f32 v51, v51, 0x3e16c740, v251
	v_fmamk_f32 v52, v52, 0x3e16c740, v251
	v_fmamk_f32 v53, v53, 0x3e16c740, v251
	v_fmamk_f32 v54, v54, 0x3e16c740, v251
	v_fmamk_f32 v55, v55, 0x3e16c740, v251
	v_fmamk_f32 v56, v56, 0x3e16c740, v251
	v_fmamk_f32 v57, v57, 0x3e16c740, v251
	v_fmamk_f32 v58, v58, 0x3e16c740, v251
	v_fmamk_f32 v59, v59, 0x3e16c740, v251
	s_waitcnt lgkmcnt(6)
	v_mfma_f32_32x32x16_bf16 v[16:31], v[130:133], v[192:195], v[16:31]
	v_fmamk_f32 v60, v60, 0x3e16c740, v251
	v_fmamk_f32 v61, v61, 0x3e16c740, v251
	v_fmamk_f32 v62, v62, 0x3e16c740, v251
	v_fmamk_f32 v63, v63, 0x3e16c740, v251
	v_exp_f32_e32 v120, v48
	v_exp_f32_e32 v135, v49
	v_exp_f32_e32 v121, v50
	v_exp_f32_e32 v134, v51
	v_exp_f32_e32 v133, v53
	v_exp_f32_e32 v132, v55
	s_waitcnt lgkmcnt(4)
	v_mfma_f32_32x32x16_bf16 v[16:31], v[122:125], v[196:199], v[16:31]
	v_exp_f32_e32 v131, v57
	v_exp_f32_e32 v130, v59
	v_exp_f32_e32 v122, v52
	v_exp_f32_e32 v123, v54
	v_exp_f32_e32 v124, v56
	v_exp_f32_e32 v125, v58
	s_waitcnt lgkmcnt(2)
	v_mfma_f32_32x32x16_bf16 v[16:31], v[126:129], v[200:203], v[16:31]
	v_exp_f32_e32 v126, v60
	v_exp_f32_e32 v129, v61
	v_exp_f32_e32 v127, v62
	v_exp_f32_e32 v128, v63
	s_waitcnt lgkmcnt(0)
	v_mfma_f32_32x32x16_bf16 v[16:31], v[184:187], v[208:211], v[16:31]
	v_cndmask_b32_e64 v184, v252, 1.0, s[6:7]
	v_cmp_gt_f32_e32 vcc, 1.0, v184
	s_barrier
	s_waitcnt vmcnt(4)
	s_waitcnt vmcnt(4)
	ds_write_b128 v173, v[96:99]
	ds_write_b128 v174, v[100:103]
	s_cbranch_vccz .LBB0_1492
	s_and_saveexec_b64 s[10:11], s[4:5]
	ds_write_b32 v167, v184 offset:128
	s_or_b64 exec, exec, s[10:11]
	s_waitcnt lgkmcnt(0)
	v_add_u32_e32 v208, v149, v146
	ds_read_b128 v[192:195], v208 offset:224
	ds_read_b128 v[196:199], v208 offset:192
	ds_read_b128 v[200:203], v208 offset:160
	ds_read_b128 v[204:207], v208 offset:128
	s_waitcnt lgkmcnt(3)
	v_pk_mul_f32 v[12:13], v[12:13], v[192:193]
	s_waitcnt lgkmcnt(2)
	v_pk_mul_f32 v[8:9], v[8:9], v[196:197]
	s_waitcnt lgkmcnt(1)
	v_pk_mul_f32 v[4:5], v[4:5], v[200:201]
	v_pk_mul_f32 v[14:15], v[14:15], v[194:195]
	v_pk_mul_f32 v[10:11], v[10:11], v[198:199]
	v_pk_mul_f32 v[6:7], v[6:7], v[202:203]
	s_waitcnt lgkmcnt(0)
	v_pk_mul_f32 v[2:3], v[2:3], v[206:207]
	v_pk_mul_f32 v[0:1], v[0:1], v[204:205]
	v_pk_mul_f32 v[28:29], v[28:29], v[192:193]
	v_pk_mul_f32 v[24:25], v[24:25], v[196:197]
	v_pk_mul_f32 v[20:21], v[20:21], v[200:201]
	v_pk_mul_f32 v[30:31], v[30:31], v[194:195]
	v_pk_mul_f32 v[26:27], v[26:27], v[198:199]
	v_pk_mul_f32 v[22:23], v[22:23], v[202:203]
	v_pk_mul_f32 v[18:19], v[18:19], v[206:207]
	v_pk_mul_f32 v[16:17], v[16:17], v[204:205]
; #define SBAR() __builtin_amdgcn_sched_barrier(0)
; #define SLOAD(i, k0) do { sr_[i].vs0 = *reinterpret_cast<const bf16x8*>(vptr + (size_t)((k0) + sr) * vstr); \
;     sr_[i].vs1 = *reinterpret_cast<const bf16x8*>(vptr + (size_t)((k0) + 32 + sr) * vstr); \
;     sr_[i].ks0 = *reinterpret_cast<const bf16x8*>(kptr + (size_t)((k0) + sr) * kstr); \
;     sr_[i].ks1 = *reinterpret_cast<const bf16x8*>(kptr + (size_t)((k0) + 32 + sr) * kstr); } while (0)
; __device__ __forceinline__ void finishSM(f32x16& p0, f32x16& p1, float alpha, float& l_reg, bf16x8& pa0, bf16x8& pa1, bf16x8& pa2, bf16x8& pa3) {
; #pragma unroll
;   for (int r = 0; r < 16; ++r) p1[r] = __builtin_amdgcn_exp2f(p1[r]);
;   float ps = 0;
; #pragma unroll
;   for (int r = 0; r < 16; ++r) ps += p0[r];
; #pragma unroll
;   for (int r = 0; r < 16; ++r) ps += p1[r];
;   { auto rr = __builtin_amdgcn_permlane32_swap(__float_as_uint(ps), __float_as_uint(ps), false, false);
;     ps = __uint_as_float(rr[0]) + __uint_as_float(rr[1]); }
;   l_reg = l_reg * alpha + ps;
;     ...
;   PK4(p0, 0, pa0); PK4(p0, 8, pa1); PK4(p1, 0, pa2); PK4(p1, 8, pa3);
; template <int NDQ, int NDV> ...
;     ...
;     SBAR(); qkt<NDQ>(pA0, pA1, K_lds, qr, r32, hi);
;     finishSM(pB0, pB1, alB, l_reg, pa0, pa1, pa2, pa3); SBAR();
;     if (j + 3 < NT) SLOAD(SE, (j + 3) * 64); SBAR();
.LBB0_1492:
	v_mov_b32_e32 v185, v253
	v_fmamk_f32 v187, v38, 0x3e16c740, v251
	v_fmamk_f32 v188, v39, 0x3e16c740, v251
	v_fmamk_f32 v195, v32, 0x3e16c740, v251
	v_fmamk_f32 v196, v33, 0x3e16c740, v251
	v_fmamk_f32 v197, v34, 0x3e16c740, v251
	v_fmamk_f32 v198, v35, 0x3e16c740, v251
	v_fmamk_f32 v199, v36, 0x3e16c740, v251
	v_fmamk_f32 v200, v37, 0x3e16c740, v251
	v_fmamk_f32 v189, v40, 0x3e16c740, v251
	v_fmamk_f32 v191, v41, 0x3e16c740, v251
	v_fmamk_f32 v192, v42, 0x3e16c740, v251
	v_fmamk_f32 v193, v43, 0x3e16c740, v251
	v_fmamk_f32 v194, v44, 0x3e16c740, v251
	v_fmamk_f32 v201, v45, 0x3e16c740, v251
	v_fmamk_f32 v202, v46, 0x3e16c740, v251
	v_fmamk_f32 v186, v47, 0x3e16c740, v251
	ds_read_b128 v[32:35], v175 offset:32768
	ds_read_b128 v[36:39], v175 offset:40960
	ds_read_b128 v[204:207], v176 offset:32768
	ds_read_b128 v[208:211], v176 offset:40960
	ds_read_b128 v[212:215], v177 offset:32768
	ds_read_b128 v[216:219], v177 offset:40960
	ds_read_b128 v[220:223], v178 offset:32768
	ds_read_b128 v[224:227], v178 offset:40960
	ds_read_b128 v[228:231], v179 offset:32768
	ds_read_b128 v[232:235], v179 offset:40960
	v_exp_f32_e32 v203, v187
	v_add_f32_e32 v187, v120, v135
	s_waitcnt lgkmcnt(9)
	v_mfma_f32_32x32x16_bf16 v[48:63], v[32:35], v[84:87], 0
	v_add_f32_e32 v187, v121, v187
	v_add_f32_e32 v187, v134, v187
	v_add_f32_e32 v187, v122, v187
	v_add_f32_e32 v187, v133, v187
	v_add_f32_e32 v187, v123, v187
	v_add_f32_e32 v187, v132, v187
	v_add_f32_e32 v187, v124, v187
	s_waitcnt lgkmcnt(8)
	v_mfma_f32_32x32x16_bf16 v[32:47], v[36:39], v[84:87], 0
	v_add_f32_e32 v187, v131, v187
	v_add_f32_e32 v187, v125, v187
	v_add_f32_e32 v187, v130, v187
	v_exp_f32_e32 v195, v195
	v_add_f32_e32 v187, v126, v187
	v_exp_f32_e32 v196, v196
	s_waitcnt lgkmcnt(7)
	v_mfma_f32_32x32x16_bf16 v[48:63], v[204:207], v[80:83], v[48:63]
	v_add_f32_e32 v187, v129, v187
	v_exp_f32_e32 v197, v197
	v_add_f32_e32 v187, v127, v187
	v_exp_f32_e32 v198, v198
	v_add_f32_e32 v187, v128, v187
	s_waitcnt lgkmcnt(6)
	v_mfma_f32_32x32x16_bf16 v[32:47], v[208:211], v[80:83], v[32:47]
	v_exp_f32_e32 v199, v199
	v_add_f32_e32 v187, v195, v187
	v_exp_f32_e32 v200, v200
	v_add_f32_e32 v187, v196, v187
	v_add_f32_e32 v187, v197, v187
	s_waitcnt lgkmcnt(5)
	v_mfma_f32_32x32x16_bf16 v[48:63], v[212:215], v[76:79], v[48:63]
	ds_read_b128 v[236:239], v180 offset:32768
	ds_read_b128 v[240:243], v180 offset:40960
	v_exp_f32_e32 v204, v188
	v_add_f32_e32 v187, v198, v187
	v_exp_f32_e32 v189, v189
	v_add_f32_e32 v187, v199, v187
	v_exp_f32_e32 v191, v191
	s_waitcnt lgkmcnt(6)
	v_mfma_f32_32x32x16_bf16 v[32:47], v[216:219], v[76:79], v[32:47]
	v_add_f32_e32 v187, v200, v187
	v_exp_f32_e32 v192, v192
	v_add_f32_e32 v187, v203, v187
	v_exp_f32_e32 v193, v193
	v_add_f32_e32 v187, v204, v187
	s_waitcnt lgkmcnt(5)
	v_mfma_f32_32x32x16_bf16 v[48:63], v[220:223], v[72:75], v[48:63]
	v_exp_f32_e32 v194, v194
	v_add_f32_e32 v187, v189, v187
	v_exp_f32_e32 v201, v201
	v_add_f32_e32 v187, v191, v187
	v_exp_f32_e32 v202, v202
	s_waitcnt lgkmcnt(4)
	v_mfma_f32_32x32x16_bf16 v[32:47], v[224:227], v[72:75], v[32:47]
	v_add_f32_e32 v187, v192, v187
	v_exp_f32_e32 v186, v186
	v_add_f32_e32 v187, v193, v187
	v_add_f32_e32 v187, v194, v187
	v_add_f32_e32 v187, v201, v187
	v_add_f32_e32 v187, v202, v187
	v_add_f32_e32 v187, v186, v187
	s_waitcnt lgkmcnt(3)
	v_mfma_f32_32x32x16_bf16 v[48:63], v[228:231], v[68:71], v[48:63]
	v_mov_b32_e32 v188, v187
	v_cvt_pk_bf16_f32 v120, v120, v135
	v_cvt_pk_bf16_f32 v121, v121, v134
	v_cvt_pk_bf16_f32 v122, v122, v133
	v_cvt_pk_bf16_f32 v123, v123, v132
	v_cvt_pk_bf16_f32 v124, v124, v131
	v_cvt_pk_bf16_f32 v125, v125, v130
	v_cvt_pk_bf16_f32 v126, v126, v129
	s_waitcnt lgkmcnt(2)
	v_mfma_f32_32x32x16_bf16 v[32:47], v[232:235], v[68:71], v[32:47]
	v_cvt_pk_bf16_f32 v127, v127, v128
	v_cvt_pk_bf16_f32 v132, v195, v196
	v_cvt_pk_bf16_f32 v133, v197, v198
	v_cvt_pk_bf16_f32 v134, v199, v200
	v_cvt_pk_bf16_f32 v135, v203, v204
	v_cvt_pk_bf16_f32 v128, v189, v191
	v_cvt_pk_bf16_f32 v129, v192, v193
	v_cvt_pk_bf16_f32 v130, v194, v201
	s_waitcnt lgkmcnt(1)
	v_mfma_f32_32x32x16_bf16 v[48:63], v[236:239], v[64:67], v[48:63]
	v_cvt_pk_bf16_f32 v131, v202, v186
	v_permlane32_swap_b32_e32 v187, v188
	v_permlane32_swap_b32_e32 v120, v122
	v_permlane32_swap_b32_e32 v121, v123
	v_permlane32_swap_b32_e32 v124, v126
	v_permlane32_swap_b32_e32 v125, v127
	v_permlane32_swap_b32_e32 v132, v134
	v_permlane32_swap_b32_e32 v133, v135
	s_waitcnt lgkmcnt(0)
	v_mfma_f32_32x32x16_bf16 v[32:47], v[240:243], v[64:67], v[32:47]
	v_permlane32_swap_b32_e32 v128, v130
	v_permlane32_swap_b32_e32 v129, v131
	s_cmp_ge_u32 s57, s56
	s_cselect_b64 s[10:11], -1, 0
	s_and_b64 vcc, exec, s[10:11]
	s_cbranch_vccnz .LBB0_1494
	v_add_co_u32_e32 v88, vcc, 0xffff0000, v154
	v_lshl_add_u64 v[92:93], v[150:151], 0, v[152:153]
	s_nop 0
	v_addc_co_u32_e32 v89, vcc, -1, v155, vcc
	global_load_dwordx4 v[96:99], v[88:89], off
	global_load_dwordx4 v[100:103], v[154:155], off
	v_lshl_add_u64 v[88:89], v[150:151], 0, v[156:157]
	global_load_dwordx4 v[88:91], v[88:89], off
	s_nop 0
	global_load_dwordx4 v[92:95], v[92:93], off

; #define SWRITE(b, i) do { *(LAS bf16x8*)(V_lds + (b) * SHM_V + vst0) = sr_[i].vs0;          \
;     *(LAS bf16x8*)(V_lds + (b) * SHM_V + vst1) = sr_[i].vs1; const int kc = sc * 2;               \
;     *(LAS bf16x8*)(K_lds + (b) * SHM_K + KSWZ(sr, kc)) = sr_[i].ks0;                       \
;     *(LAS bf16x8*)(K_lds + (b) * SHM_K + KSWZ(32 + sr, kc)) = sr_[i].ks1; } while (0)
; #define SWAIT() asm volatile("s_waitcnt vmcnt(4)" ::: "memory")
; #define RESC(a) do { if (__any((a) < 1.f)) { if (hi == 0) al_l[r32] = (a); asm volatile("s_waitcnt lgkmcnt(0)" ::: "memory"); \
;     _Pragma("unroll") for (int d = 0; d < NDV; ++d) _Pragma("unroll") for (int r = 0; r < 16; ++r) o[d][r] *= al_l[crow(r, hi)]; } } while (0)
; __device__ __forceinline__ void partialSM(f32x16& p0, f32x16& p1, float& m_reg, float& mn, float& alpha, float C, float thr) {
;     ...
;   if (__builtin_expect(__all(pmax - m_reg <= thr), 1)) { mn = m_reg; alpha = 1.f; }
;   else { mn = fmaxf(m_reg, pmax); alpha = __builtin_amdgcn_exp2f((m_reg - mn) * C); m_reg = mn; }
;   const float mnC = -mn * C;
; #pragma unroll
;   for (int r = 0; r < 16; ++r) p0[r] = fmaf(p0[r], C, mnC);
; #pragma unroll
;   for (int r = 0; r < 16; ++r) p1[r] = fmaf(p1[r], C, mnC);
; #pragma unroll
;   for (int r = 0; r < 16; ++r) p0[r] = __builtin_amdgcn_exp2f(p0[r]);
; template <int NDQ, int NDV> ...
;     ...
;     pv_d0<NDV>(o, vb0 + SHM_V, pa0, pa1, pa2, pa3); partialSM(pA0, pA1, m_reg, mnA, alA, Cs, thr);
;     __syncthreads(); SWAIT(); SWRITE(1, SO);
;     RESC(alA); __syncthreads();
.Lmla_backB:
	v_cndmask_b32_e64 v253, v186, v185, s[6:7]
	v_mul_f32_e32 v250, 0xbe16c740, v253
	s_waitcnt lgkmcnt(8)
	v_mfma_f32_32x32x16_bf16 v[0:15], v[128:131], v[204:207], v[0:15]
	v_fmamk_f32 v48, v48, 0x3e16c740, v250
	v_fmamk_f32 v49, v49, 0x3e16c740, v250
	v_fmamk_f32 v50, v50, 0x3e16c740, v250
	v_fmamk_f32 v51, v51, 0x3e16c740, v250
	v_fmamk_f32 v52, v52, 0x3e16c740, v250
	v_fmamk_f32 v53, v53, 0x3e16c740, v250
	v_fmamk_f32 v54, v54, 0x3e16c740, v250
	v_fmamk_f32 v55, v55, 0x3e16c740, v250
	v_fmamk_f32 v56, v56, 0x3e16c740, v250
	v_fmamk_f32 v57, v57, 0x3e16c740, v250
	v_fmamk_f32 v58, v58, 0x3e16c740, v250
	v_fmamk_f32 v59, v59, 0x3e16c740, v250
	s_waitcnt lgkmcnt(6)
	v_mfma_f32_32x32x16_bf16 v[16:31], v[120:123], v[192:195], v[16:31]
	v_fmamk_f32 v60, v60, 0x3e16c740, v250
	v_fmamk_f32 v61, v61, 0x3e16c740, v250
	v_fmamk_f32 v62, v62, 0x3e16c740, v250
	v_fmamk_f32 v63, v63, 0x3e16c740, v250
	v_exp_f32_e32 v185, v53
	v_exp_f32_e32 v186, v55
	v_exp_f32_e32 v122, v56
	v_exp_f32_e32 v123, v58
	s_waitcnt lgkmcnt(4)
	v_mfma_f32_32x32x16_bf16 v[16:31], v[124:127], v[196:199], v[16:31]
	v_exp_f32_e32 v124, v60
	v_exp_f32_e32 v125, v57
	v_exp_f32_e32 v126, v59
	v_exp_f32_e32 v127, v61
	s_waitcnt lgkmcnt(2)
	v_mfma_f32_32x32x16_bf16 v[16:31], v[132:135], v[200:203], v[16:31]
	v_exp_f32_e32 v132, v52
	v_exp_f32_e32 v133, v54
	v_exp_f32_e32 v134, v49
	v_exp_f32_e32 v135, v51
	s_waitcnt lgkmcnt(0)
	v_mfma_f32_32x32x16_bf16 v[16:31], v[128:131], v[208:211], v[16:31]
	v_exp_f32_e32 v128, v62
	v_exp_f32_e32 v129, v63
	v_exp_f32_e32 v130, v48
	v_exp_f32_e32 v131, v50
	v_cndmask_b32_e64 v121, v252, 1.0, s[6:7]
	v_cmp_gt_f32_e32 vcc, 1.0, v121
	s_barrier
	s_waitcnt vmcnt(4)
	s_cmp_lg_u64 s[10:11], 0
	s_cbranch_scc0 .Lmla_nodrain
	s_waitcnt vmcnt(0)
.Lmla_nodrain:
	ds_write_b128 v173, v[104:107] offset:16384
	ds_write_b128 v174, v[108:111] offset:16384
	s_cbranch_vccz .LBB0_1498
	s_and_saveexec_b64 s[12:13], s[4:5]
	ds_write_b32 v167, v121 offset:128
	s_or_b64 exec, exec, s[12:13]
	s_waitcnt lgkmcnt(0)
	v_add_u32_e32 v116, v149, v146
	ds_read_b128 v[104:107], v116 offset:224
	ds_read_b128 v[108:111], v116 offset:192
	ds_read_b128 v[112:115], v116 offset:160
	ds_read_b128 v[116:119], v116 offset:128
	s_waitcnt lgkmcnt(3)
	v_pk_mul_f32 v[12:13], v[12:13], v[104:105]
	s_waitcnt lgkmcnt(2)
	v_pk_mul_f32 v[8:9], v[8:9], v[108:109]
	s_waitcnt lgkmcnt(1)
	v_pk_mul_f32 v[4:5], v[4:5], v[112:113]
	v_pk_mul_f32 v[14:15], v[14:15], v[106:107]
	v_pk_mul_f32 v[10:11], v[10:11], v[110:111]
	v_pk_mul_f32 v[6:7], v[6:7], v[114:115]
	s_waitcnt lgkmcnt(0)
	v_pk_mul_f32 v[2:3], v[2:3], v[118:119]
	v_pk_mul_f32 v[0:1], v[0:1], v[116:117]
	v_pk_mul_f32 v[28:29], v[28:29], v[104:105]
	v_pk_mul_f32 v[24:25], v[24:25], v[108:109]
	v_pk_mul_f32 v[20:21], v[20:21], v[112:113]
	v_pk_mul_f32 v[30:31], v[30:31], v[106:107]
	v_pk_mul_f32 v[26:27], v[26:27], v[110:111]
	v_pk_mul_f32 v[22:23], v[22:23], v[114:115]
	v_pk_mul_f32 v[18:19], v[18:19], v[118:119]
	v_pk_mul_f32 v[16:17], v[16:17], v[116:117]

; #define SBAR() __builtin_amdgcn_sched_barrier(0)
; #define SLOAD(i, k0) do { sr_[i].vs0 = *reinterpret_cast<const bf16x8*>(vptr + (size_t)((k0) + sr) * vstr); \
;     sr_[i].vs1 = *reinterpret_cast<const bf16x8*>(vptr + (size_t)((k0) + 32 + sr) * vstr); \
;     sr_[i].ks0 = *reinterpret_cast<const bf16x8*>(kptr + (size_t)((k0) + sr) * kstr); \
;     sr_[i].ks1 = *reinterpret_cast<const bf16x8*>(kptr + (size_t)((k0) + 32 + sr) * kstr); } while (0)
; __device__ __forceinline__ void finishSM(f32x16& p0, f32x16& p1, float alpha, float& l_reg, bf16x8& pa0, bf16x8& pa1, bf16x8& pa2, bf16x8& pa3) {
; #pragma unroll
;   for (int r = 0; r < 16; ++r) p1[r] = __builtin_amdgcn_exp2f(p1[r]);
;   float ps = 0;
; #pragma unroll
;   for (int r = 0; r < 16; ++r) ps += p0[r];
; #pragma unroll
;   for (int r = 0; r < 16; ++r) ps += p1[r];
;   { auto rr = __builtin_amdgcn_permlane32_swap(__float_as_uint(ps), __float_as_uint(ps), false, false);
;     ps = __uint_as_float(rr[0]) + __uint_as_float(rr[1]); }
;   l_reg = l_reg * alpha + ps;
;     ...
;   PK4(p0, 0, pa0); PK4(p0, 8, pa1); PK4(p1, 0, pa2); PK4(p1, 8, pa3);
; template <int NDQ, int NDV> ...
;     ...
;     SBAR(); qkt<NDQ>(pB0, pB1, K_lds + SHM_K, qr, r32, hi);
;     finishSM(pA0, pA1, alA, l_reg, pa0, pa1, pa2, pa3); SBAR();
;     SLOAD(SO, (j + 2) * 64); SBAR();
;     pv_d0<NDV>(o, vb0, pa0, pa1, pa2, pa3); partialSM(pB0, pB1, m_reg, mnB, alB, Cs, thr);
.LBB0_2123:
	ds_read_b128 v[64:67], v199 offset:49152
	ds_read_b128 v[68:71], v199 offset:57344
	ds_read_b128 v[216:219], v200 offset:49152
	ds_read_b128 v[220:223], v200 offset:57344
	v_add_f32_e32 v161, v236, v237
	s_waitcnt lgkmcnt(3)
	v_mfma_f32_32x32x16_bf16 v[80:95], v[64:67], v[124:127], 0
	v_add_f32_e32 v161, v238, v161
	v_add_f32_e32 v161, v239, v161
	v_add_f32_e32 v161, v240, v161
	v_add_f32_e32 v161, v241, v161
	v_add_f32_e32 v161, v242, v161
	v_add_f32_e32 v161, v243, v161
	s_waitcnt lgkmcnt(2)
	v_mfma_f32_32x32x16_bf16 v[64:79], v[68:71], v[124:127], 0
	v_add_f32_e32 v161, v244, v161
	v_add_f32_e32 v161, v245, v161
	v_add_f32_e32 v161, v246, v161
	v_add_f32_e32 v161, v247, v161
	v_exp_f32_e32 v154, v154
	s_waitcnt lgkmcnt(1)
	v_mfma_f32_32x32x16_bf16 v[80:95], v[216:219], v[120:123], v[80:95]
	v_add_f32_e32 v161, v248, v161
	v_exp_f32_e32 v155, v155
	v_add_f32_e32 v161, v249, v161
	v_exp_f32_e32 v152, v152
	s_waitcnt lgkmcnt(0)
	v_mfma_f32_32x32x16_bf16 v[64:79], v[220:223], v[120:123], v[64:79]
	ds_read_b128 v[216:219], v201 offset:49152
	ds_read_b128 v[220:223], v201 offset:57344
	v_add_f32_e32 v161, v250, v161
	v_exp_f32_e32 v153, v153
	v_add_f32_e32 v161, v251, v161
	v_exp_f32_e32 v148, v148
	s_waitcnt lgkmcnt(1)
	v_mfma_f32_32x32x16_bf16 v[80:95], v[216:219], v[116:119], v[80:95]
	v_add_f32_e32 v161, v154, v161
	v_exp_f32_e32 v149, v149
	v_add_f32_e32 v161, v155, v161
	v_exp_f32_e32 v146, v146
	s_waitcnt lgkmcnt(0)
	v_mfma_f32_32x32x16_bf16 v[64:79], v[220:223], v[116:119], v[64:79]
	ds_read_b128 v[216:219], v202 offset:49152
	ds_read_b128 v[220:223], v202 offset:57344
	v_add_f32_e32 v161, v152, v161
	v_exp_f32_e32 v147, v147
	v_add_f32_e32 v161, v153, v161
	v_exp_f32_e32 v144, v144
	s_waitcnt lgkmcnt(1)
	v_mfma_f32_32x32x16_bf16 v[80:95], v[216:219], v[112:115], v[80:95]
	v_add_f32_e32 v161, v148, v161
	v_exp_f32_e32 v145, v145
	v_add_f32_e32 v161, v149, v161
	v_exp_f32_e32 v158, v158
	s_waitcnt lgkmcnt(0)
	v_mfma_f32_32x32x16_bf16 v[64:79], v[220:223], v[112:115], v[64:79]
	ds_read_b128 v[216:219], v203 offset:49152
	ds_read_b128 v[220:223], v203 offset:57344
	v_add_f32_e32 v161, v146, v161
	v_exp_f32_e32 v159, v159
	v_add_f32_e32 v161, v147, v161
	v_exp_f32_e32 v156, v156
	s_waitcnt lgkmcnt(1)
	v_mfma_f32_32x32x16_bf16 v[80:95], v[216:219], v[108:111], v[80:95]
	v_add_f32_e32 v161, v144, v161
	v_exp_f32_e32 v157, v157
	v_add_f32_e32 v161, v145, v161
	v_exp_f32_e32 v150, v150
	s_waitcnt lgkmcnt(0)
	v_mfma_f32_32x32x16_bf16 v[64:79], v[220:223], v[108:111], v[64:79]
	ds_read_b128 v[216:219], v204 offset:49152
	ds_read_b128 v[220:223], v204 offset:57344
	v_add_f32_e32 v161, v158, v161
	v_exp_f32_e32 v151, v151
	v_add_f32_e32 v161, v159, v161
	v_add_f32_e32 v161, v156, v161
	v_add_f32_e32 v161, v157, v161
	s_waitcnt lgkmcnt(1)
	v_mfma_f32_32x32x16_bf16 v[80:95], v[216:219], v[104:107], v[80:95]
	v_add_f32_e32 v161, v150, v161
	v_add_f32_e32 v208, v151, v161
	v_mov_b32_e32 v209, v208
	v_cvt_pk_bf16_f32 v210, v236, v237
	v_cvt_pk_bf16_f32 v211, v238, v239
	v_cvt_pk_bf16_f32 v212, v240, v241
	s_waitcnt lgkmcnt(0)
	v_mfma_f32_32x32x16_bf16 v[64:79], v[220:223], v[104:107], v[64:79]
	ds_read_b128 v[216:219], v205 offset:49152
	ds_read_b128 v[220:223], v205 offset:57344
	v_permlane32_swap_b32_e32 v208, v209
	v_cvt_pk_bf16_f32 v213, v242, v243
	v_cvt_pk_bf16_f32 v170, v244, v245
	v_cvt_pk_bf16_f32 v171, v246, v247
	v_permlane32_swap_b32_e32 v210, v212
	v_cvt_pk_bf16_f32 v172, v248, v249
	s_waitcnt lgkmcnt(1)
	v_mfma_f32_32x32x16_bf16 v[80:95], v[216:219], v[100:103], v[80:95]
	v_cvt_pk_bf16_f32 v173, v250, v251
	v_cvt_pk_bf16_f32 v162, v154, v155
	v_cvt_pk_bf16_f32 v163, v152, v153
	v_cvt_pk_bf16_f32 v164, v148, v149
	v_cvt_pk_bf16_f32 v165, v146, v147
	v_cvt_pk_bf16_f32 v166, v144, v145
	s_waitcnt lgkmcnt(0)
	v_mfma_f32_32x32x16_bf16 v[64:79], v[220:223], v[100:103], v[64:79]
	ds_read_b128 v[216:219], v206 offset:49152
	ds_read_b128 v[220:223], v206 offset:57344
	v_cvt_pk_bf16_f32 v167, v158, v159
	v_cvt_pk_bf16_f32 v168, v156, v157
	v_cvt_pk_bf16_f32 v169, v150, v151
	v_permlane32_swap_b32_e32 v211, v213
	v_permlane32_swap_b32_e32 v170, v172
	v_permlane32_swap_b32_e32 v171, v173
	s_waitcnt lgkmcnt(1)
	v_mfma_f32_32x32x16_bf16 v[80:95], v[216:219], v[96:99], v[80:95]
	v_permlane32_swap_b32_e32 v162, v164
	v_permlane32_swap_b32_e32 v163, v165
	v_permlane32_swap_b32_e32 v166, v168
	v_permlane32_swap_b32_e32 v167, v169
	s_waitcnt lgkmcnt(0)
	v_mfma_f32_32x32x16_bf16 v[64:79], v[220:223], v[96:99], v[64:79]
	v_add_co_u32_e32 v148, vcc, s50, v184
	s_nop 1
	v_addc_co_u32_e32 v149, vcc, -1, v185, vcc
	v_add_co_u32_e32 v152, vcc, s51, v184
	s_nop 1
	v_addc_co_u32_e32 v153, vcc, -1, v185, vcc
	global_load_dwordx4 v[144:147], v[148:149], off
	s_nop 0
	global_load_dwordx4 v[148:151], v[148:149], off offset:-512
	s_nop 0
	global_load_dwordx4 v[156:159], v[152:153], off
	s_nop 0
	global_load_dwordx4 v[152:155], v[152:153], off offset:-512
	s_waitcnt vmcnt(4)
	ds_write_b128 v195, v[140:143] offset:32768
	ds_write_b128 v196, v[132:135] offset:32768
	ds_read_b64_tr_b16 v[214:215], v194 offset:0
	ds_read_b64_tr_b16 v[216:217], v194 offset:0x800
	ds_read_b64_tr_b16 v[218:219], v194 offset:0x1000
	ds_read_b64_tr_b16 v[220:221], v194 offset:0x1800
	ds_read_b64_tr_b16 v[222:223], v194 offset:0x2000
	ds_read_b64_tr_b16 v[224:225], v194 offset:0x2800
	ds_read_b64_tr_b16 v[226:227], v194 offset:0x3000
	ds_read_b64_tr_b16 v[228:229], v194 offset:0x3800
	s_waitcnt lgkmcnt(6)
; #define SWRITE(b, i) do { *(LAS bf16x8*)(V_lds + (b) * SHM_V + vst0) = sr_[i].vs0;          \
;     *(LAS bf16x8*)(V_lds + (b) * SHM_V + vst1) = sr_[i].vs1; const int kc = sc * 2;               \
;     *(LAS bf16x8*)(K_lds + (b) * SHM_K + KSWZ(sr, kc)) = sr_[i].ks0;                       \
;     *(LAS bf16x8*)(K_lds + (b) * SHM_K + KSWZ(32 + sr, kc)) = sr_[i].ks1; } while (0)
; #define SWAIT() asm volatile("s_waitcnt vmcnt(4)" ::: "memory")
; #define RESC(a) do { if (__any((a) < 1.f)) { if (hi == 0) al_l[r32] = (a); asm volatile("s_waitcnt lgkmcnt(0)" ::: "memory"); \
;     _Pragma("unroll") for (int d = 0; d < NDV; ++d) _Pragma("unroll") for (int r = 0; r < 16; ++r) o[d][r] *= al_l[crow(r, hi)]; } } while (0)
; __device__ __forceinline__ void partialSM(f32x16& p0, f32x16& p1, float& m_reg, float& mn, float& alpha, float C, float thr) {
;   float pmax = p0[0];
; #pragma unroll
;   for (int r = 1; r < 16; ++r) pmax = fmaxf(pmax, p0[r]);
; #pragma unroll
;   for (int r = 0; r < 16; ++r) pmax = fmaxf(pmax, p1[r]);
;   { auto rr = __builtin_amdgcn_permlane32_swap(__float_as_uint(pmax), __float_as_uint(pmax), false, false);
;     pmax = fmaxf(__uint_as_float(rr[0]), __uint_as_float(rr[1])); }
;   if (__builtin_expect(__all(pmax - m_reg <= thr), 1)) { mn = m_reg; alpha = 1.f; }
;   else { mn = fmaxf(m_reg, pmax); alpha = __builtin_amdgcn_exp2f((m_reg - mn) * C); m_reg = mn; }
;   const float mnC = -mn * C;
; #pragma unroll
;   for (int r = 0; r < 16; ++r) p0[r] = fmaf(p0[r], C, mnC);
; #pragma unroll
;   for (int r = 0; r < 16; ++r) p1[r] = fmaf(p1[r], C, mnC);
; #pragma unroll
;   for (int r = 0; r < 16; ++r) p0[r] = __builtin_amdgcn_exp2f(p0[r]);
; template <int NDQ, int NDV> ...
;     ...
;     pv_d0<NDV>(o, vb0, pa0, pa1, pa2, pa3); partialSM(pB0, pB1, m_reg, mnB, alB, Cs, thr);
;     __syncthreads(); SWAIT(); SWRITE(0, SE);
;     RESC(alB); __syncthreads();
	v_mfma_f32_32x32x16_bf16 v[0:15], v[210:213], v[214:217], v[0:15]
	ds_read_b64_tr_b16 v[214:215], v194 offset:0x200
	ds_read_b64_tr_b16 v[216:217], v194 offset:0xa00
	v_max_f32_e32 v161, v80, v81
	v_max3_f32 v161, v161, v82, v83
	v_max3_f32 v161, v161, v84, v85
	v_max3_f32 v161, v161, v86, v87
	v_max3_f32 v161, v161, v88, v89
	v_max3_f32 v161, v161, v90, v91
	s_waitcnt lgkmcnt(6)
	v_mfma_f32_32x32x16_bf16 v[0:15], v[170:173], v[218:221], v[0:15]
	ds_read_b64_tr_b16 v[218:219], v194 offset:0x1200
	ds_read_b64_tr_b16 v[220:221], v194 offset:0x1a00
	v_max3_f32 v161, v161, v92, v93
	v_max3_f32 v161, v161, v94, v95
	v_max3_f32 v161, v161, v64, v65
	v_max3_f32 v161, v161, v66, v67
	v_max3_f32 v161, v161, v68, v69
	v_max3_f32 v161, v161, v70, v71
	s_waitcnt lgkmcnt(6)
	v_mfma_f32_32x32x16_bf16 v[0:15], v[162:165], v[222:225], v[0:15]
	ds_read_b64_tr_b16 v[222:223], v194 offset:0x2200
	ds_read_b64_tr_b16 v[224:225], v194 offset:0x2a00
	ds_read_b64_tr_b16 v[230:231], v194 offset:0x3200
	ds_read_b64_tr_b16 v[232:233], v194 offset:0x3a00
	v_max3_f32 v161, v161, v72, v73
	v_max3_f32 v161, v161, v74, v75
	v_max3_f32 v161, v161, v76, v77
	v_max3_f32 v161, v161, v78, v79
	v_mov_b32_e32 v174, v161
	s_nop 1
	s_waitcnt lgkmcnt(8)
	v_mfma_f32_32x32x16_bf16 v[0:15], v[166:169], v[226:229], v[0:15]
	v_permlane32_swap_b32_e32 v161, v174
	v_max_f32_e32 v161, v161, v174
	v_sub_f32_e32 v175, v161, v160
	v_max_f32_e32 v161, v160, v161
	v_cmp_ge_f32_e32 vcc, s48, v175
	s_cmp_eq_u64 vcc, exec
	s_waitcnt lgkmcnt(6)
	v_mfma_f32_32x32x16_bf16 v[48:63], v[210:213], v[214:217], v[48:63]
	ds_read_b64_tr_b16 v[214:215], v194 offset:0x400
	ds_read_b64_tr_b16 v[216:217], v194 offset:0xc00
	s_cselect_b64 s[2:3], -1, 0
	s_cbranch_scc0 .Lgqa_rareA
.Lgqa_backA:
	v_cndmask_b32_e64 v234, v161, v160, s[2:3]
	v_mul_f32_e32 v175, 0xbe0293ee, v234
	v_fmamk_f32 v80, v80, 0x3e0293ee, v175
	s_waitcnt lgkmcnt(6)
	v_mfma_f32_32x32x16_bf16 v[48:63], v[170:173], v[218:221], v[48:63]
	ds_read_b64_tr_b16 v[218:219], v194 offset:0x1400
	ds_read_b64_tr_b16 v[220:221], v194 offset:0x1c00
	v_fmamk_f32 v81, v81, 0x3e0293ee, v175
	v_fmamk_f32 v82, v82, 0x3e0293ee, v175
	v_fmamk_f32 v83, v83, 0x3e0293ee, v175
	v_fmamk_f32 v84, v84, 0x3e0293ee, v175
	v_fmamk_f32 v85, v85, 0x3e0293ee, v175
	v_fmamk_f32 v86, v86, 0x3e0293ee, v175
	s_waitcnt lgkmcnt(6)
	v_mfma_f32_32x32x16_bf16 v[48:63], v[162:165], v[222:225], v[48:63]
	ds_read_b64_tr_b16 v[222:223], v194 offset:0x2400
	ds_read_b64_tr_b16 v[224:225], v194 offset:0x2c00
	ds_read_b64_tr_b16 v[226:227], v194 offset:0x3400
	ds_read_b64_tr_b16 v[228:229], v194 offset:0x3c00
	v_fmamk_f32 v87, v87, 0x3e0293ee, v175
	v_fmamk_f32 v88, v88, 0x3e0293ee, v175
	v_fmamk_f32 v89, v89, 0x3e0293ee, v175
	v_fmamk_f32 v90, v90, 0x3e0293ee, v175
	v_fmamk_f32 v91, v91, 0x3e0293ee, v175
	v_fmamk_f32 v92, v92, 0x3e0293ee, v175
	s_waitcnt lgkmcnt(8)
	v_mfma_f32_32x32x16_bf16 v[48:63], v[166:169], v[230:233], v[48:63]
	v_fmamk_f32 v93, v93, 0x3e0293ee, v175
	v_fmamk_f32 v94, v94, 0x3e0293ee, v175
	v_fmamk_f32 v95, v95, 0x3e0293ee, v175
	v_exp_f32_e32 v236, v80
	s_waitcnt lgkmcnt(6)
	v_mfma_f32_32x32x16_bf16 v[32:47], v[210:213], v[214:217], v[32:47]
	ds_read_b64_tr_b16 v[214:215], v194 offset:0x600
	ds_read_b64_tr_b16 v[216:217], v194 offset:0xe00
	v_exp_f32_e32 v237, v81
	v_exp_f32_e32 v238, v82
	v_exp_f32_e32 v239, v83
	s_waitcnt lgkmcnt(6)
	v_mfma_f32_32x32x16_bf16 v[32:47], v[170:173], v[218:221], v[32:47]
	ds_read_b64_tr_b16 v[218:219], v194 offset:0x1600
	ds_read_b64_tr_b16 v[220:221], v194 offset:0x1e00
	v_exp_f32_e32 v240, v84
	v_exp_f32_e32 v241, v85
	v_exp_f32_e32 v242, v86
	s_waitcnt lgkmcnt(6)
	v_mfma_f32_32x32x16_bf16 v[32:47], v[162:165], v[222:225], v[32:47]
	ds_read_b64_tr_b16 v[222:223], v194 offset:0x2600
	ds_read_b64_tr_b16 v[224:225], v194 offset:0x2e00
	ds_read_b64_tr_b16 v[230:231], v194 offset:0x3600
	ds_read_b64_tr_b16 v[232:233], v194 offset:0x3e00
	v_exp_f32_e32 v243, v87
	v_exp_f32_e32 v244, v88
	v_exp_f32_e32 v245, v89
	s_waitcnt lgkmcnt(8)
	v_mfma_f32_32x32x16_bf16 v[32:47], v[166:169], v[226:229], v[32:47]
	v_exp_f32_e32 v246, v90
	v_exp_f32_e32 v247, v91
	v_exp_f32_e32 v248, v92
	s_waitcnt lgkmcnt(6)
	v_mfma_f32_32x32x16_bf16 v[16:31], v[210:213], v[214:217], v[16:31]
	v_exp_f32_e32 v249, v93
	v_exp_f32_e32 v250, v94
	v_exp_f32_e32 v251, v95
	s_waitcnt lgkmcnt(4)
	v_mfma_f32_32x32x16_bf16 v[16:31], v[170:173], v[218:221], v[16:31]
	s_waitcnt lgkmcnt(2)
	v_mfma_f32_32x32x16_bf16 v[16:31], v[162:165], v[222:225], v[16:31]
	s_waitcnt lgkmcnt(0)
	v_mfma_f32_32x32x16_bf16 v[16:31], v[166:169], v[230:233], v[16:31]
	v_cndmask_b32_e64 v210, v235, 1.0, s[2:3]
	v_cmp_gt_f32_e32 vcc, 1.0, v210
	s_barrier
	s_waitcnt vmcnt(4)
	s_waitcnt vmcnt(4)
	ds_write_b128 v197, v[128:131]
	ds_write_b128 v198, v[136:139]
	s_cbranch_vccz .LBB0_2127
	s_and_saveexec_b64 s[30:31], s[0:1]
	ds_write_b32 v191, v210 offset:128
	s_or_b64 exec, exec, s[30:31]
	s_waitcnt lgkmcnt(0)
	v_add_u32_e32 v174, v183, v176
	ds_read_b128 v[162:165], v174 offset:224
	ds_read_b128 v[166:169], v174 offset:192
	ds_read_b128 v[170:173], v174 offset:160
	ds_read_b128 v[212:215], v174 offset:128
	s_waitcnt lgkmcnt(3)
	v_pk_mul_f32 v[12:13], v[12:13], v[162:163]
	s_waitcnt lgkmcnt(2)
	v_pk_mul_f32 v[8:9], v[8:9], v[166:167]
	s_waitcnt lgkmcnt(1)
	v_pk_mul_f32 v[4:5], v[4:5], v[170:171]
	v_pk_mul_f32 v[14:15], v[14:15], v[164:165]
	v_pk_mul_f32 v[10:11], v[10:11], v[168:169]
	v_pk_mul_f32 v[6:7], v[6:7], v[172:173]
	s_waitcnt lgkmcnt(0)
	v_pk_mul_f32 v[2:3], v[2:3], v[214:215]
	v_pk_mul_f32 v[0:1], v[0:1], v[212:213]
	v_pk_mul_f32 v[60:61], v[60:61], v[162:163]
	v_pk_mul_f32 v[56:57], v[56:57], v[166:167]
	v_pk_mul_f32 v[52:53], v[52:53], v[170:171]
	v_pk_mul_f32 v[62:63], v[62:63], v[164:165]
	v_pk_mul_f32 v[58:59], v[58:59], v[168:169]
	v_pk_mul_f32 v[54:55], v[54:55], v[172:173]
	v_pk_mul_f32 v[50:51], v[50:51], v[214:215]
	v_pk_mul_f32 v[48:49], v[48:49], v[212:213]
	v_pk_mul_f32 v[44:45], v[44:45], v[162:163]
	v_pk_mul_f32 v[40:41], v[40:41], v[166:167]
	v_pk_mul_f32 v[36:37], v[36:37], v[170:171]
	v_pk_mul_f32 v[46:47], v[46:47], v[164:165]
	v_pk_mul_f32 v[42:43], v[42:43], v[168:169]
	v_pk_mul_f32 v[38:39], v[38:39], v[172:173]
	v_pk_mul_f32 v[34:35], v[34:35], v[214:215]
	v_pk_mul_f32 v[32:33], v[32:33], v[212:213]
	v_pk_mul_f32 v[28:29], v[28:29], v[162:163]
	v_pk_mul_f32 v[24:25], v[24:25], v[166:167]
	v_pk_mul_f32 v[20:21], v[20:21], v[170:171]
	v_pk_mul_f32 v[30:31], v[30:31], v[164:165]
	v_pk_mul_f32 v[26:27], v[26:27], v[168:169]
	v_pk_mul_f32 v[22:23], v[22:23], v[172:173]
	v_pk_mul_f32 v[18:19], v[18:19], v[214:215]
	v_pk_mul_f32 v[16:17], v[16:17], v[212:213]
; #define SBAR() __builtin_amdgcn_sched_barrier(0)
; #define SLOAD(i, k0) do { sr_[i].vs0 = *reinterpret_cast<const bf16x8*>(vptr + (size_t)((k0) + sr) * vstr); \
;     sr_[i].vs1 = *reinterpret_cast<const bf16x8*>(vptr + (size_t)((k0) + 32 + sr) * vstr); \
;     sr_[i].ks0 = *reinterpret_cast<const bf16x8*>(kptr + (size_t)((k0) + sr) * kstr); \
;     sr_[i].ks1 = *reinterpret_cast<const bf16x8*>(kptr + (size_t)((k0) + 32 + sr) * kstr); } while (0)
; __device__ __forceinline__ void finishSM(f32x16& p0, f32x16& p1, float alpha, float& l_reg, bf16x8& pa0, bf16x8& pa1, bf16x8& pa2, bf16x8& pa3) {
; #pragma unroll
;   for (int r = 0; r < 16; ++r) p1[r] = __builtin_amdgcn_exp2f(p1[r]);
;   float ps = 0;
; #pragma unroll
;   for (int r = 0; r < 16; ++r) ps += p0[r];
; #pragma unroll
;   for (int r = 0; r < 16; ++r) ps += p1[r];
;   { auto rr = __builtin_amdgcn_permlane32_swap(__float_as_uint(ps), __float_as_uint(ps), false, false);
;     ps = __uint_as_float(rr[0]) + __uint_as_float(rr[1]); }
;   l_reg = l_reg * alpha + ps;
;     ...
;   PK4(p0, 0, pa0); PK4(p0, 8, pa1); PK4(p1, 0, pa2); PK4(p1, 8, pa3);
; template <int NDQ, int NDV> ...
;     ...
;     SBAR(); qkt<NDQ>(pA0, pA1, K_lds, qr, r32, hi);
;     finishSM(pB0, pB1, alB, l_reg, pa0, pa1, pa2, pa3); SBAR();
;     if (j + 3 < NT) SLOAD(SE, (j + 3) * 64); SBAR();
.LBB0_2127:
	v_mov_b32_e32 v211, v234
	v_fmamk_f32 v221, v64, 0x3e0293ee, v175
	v_fmamk_f32 v222, v65, 0x3e0293ee, v175
	v_fmamk_f32 v223, v66, 0x3e0293ee, v175
	v_fmamk_f32 v224, v67, 0x3e0293ee, v175
	v_fmamk_f32 v225, v68, 0x3e0293ee, v175
	v_fmamk_f32 v214, v69, 0x3e0293ee, v175
	v_fmamk_f32 v215, v70, 0x3e0293ee, v175
	v_fmamk_f32 v216, v71, 0x3e0293ee, v175
	v_fmamk_f32 v217, v72, 0x3e0293ee, v175
	v_fmamk_f32 v218, v73, 0x3e0293ee, v175
	v_fmamk_f32 v219, v74, 0x3e0293ee, v175
	v_fmamk_f32 v220, v75, 0x3e0293ee, v175
	v_fmamk_f32 v213, v76, 0x3e0293ee, v175
	v_fmamk_f32 v226, v77, 0x3e0293ee, v175
	v_fmamk_f32 v227, v78, 0x3e0293ee, v175
	v_fmamk_f32 v212, v79, 0x3e0293ee, v175
	s_add_i32 s61, s61, 2
	ds_read_b128 v[64:67], v199 offset:32768
	ds_read_b128 v[68:71], v199 offset:40960
	ds_read_b128 v[228:231], v200 offset:32768
	ds_read_b128 v[232:235], v200 offset:40960
	v_exp_f32_e32 v221, v221
	s_waitcnt lgkmcnt(3)
	v_mfma_f32_32x32x16_bf16 v[80:95], v[64:67], v[124:127], 0
	v_exp_f32_e32 v222, v222
	v_exp_f32_e32 v223, v223
	v_exp_f32_e32 v224, v224
	s_waitcnt lgkmcnt(2)
	v_mfma_f32_32x32x16_bf16 v[64:79], v[68:71], v[124:127], 0
	v_exp_f32_e32 v225, v225
	v_exp_f32_e32 v214, v214
	v_exp_f32_e32 v215, v215
	s_waitcnt lgkmcnt(1)
	v_mfma_f32_32x32x16_bf16 v[80:95], v[228:231], v[120:123], v[80:95]
	v_exp_f32_e32 v216, v216
	v_exp_f32_e32 v217, v217
	v_exp_f32_e32 v218, v218
	s_waitcnt lgkmcnt(0)
	v_mfma_f32_32x32x16_bf16 v[64:79], v[232:235], v[120:123], v[64:79]
	ds_read_b128 v[228:231], v201 offset:32768
	ds_read_b128 v[232:235], v201 offset:40960
	v_exp_f32_e32 v219, v219
	v_exp_f32_e32 v220, v220
	v_exp_f32_e32 v226, v226
	s_waitcnt lgkmcnt(1)
	v_mfma_f32_32x32x16_bf16 v[80:95], v[228:231], v[116:119], v[80:95]
	v_exp_f32_e32 v227, v227
	v_exp_f32_e32 v253, v212
	v_exp_f32_e32 v252, v213
	s_waitcnt lgkmcnt(0)
	v_mfma_f32_32x32x16_bf16 v[64:79], v[232:235], v[116:119], v[64:79]
	ds_read_b128 v[228:231], v202 offset:32768
	ds_read_b128 v[232:235], v202 offset:40960
	v_add_f32_e32 v212, v236, v237
	v_add_f32_e32 v212, v238, v212
	v_add_f32_e32 v212, v239, v212
	v_add_f32_e32 v212, v240, v212
	v_add_f32_e32 v212, v241, v212
	s_waitcnt lgkmcnt(1)
	v_mfma_f32_32x32x16_bf16 v[80:95], v[228:231], v[112:115], v[80:95]
	v_add_f32_e32 v212, v242, v212
	v_add_f32_e32 v212, v243, v212
	v_add_f32_e32 v212, v244, v212
	v_add_f32_e32 v212, v245, v212
	v_add_f32_e32 v212, v246, v212
	v_add_f32_e32 v212, v247, v212
	s_waitcnt lgkmcnt(0)
	v_mfma_f32_32x32x16_bf16 v[64:79], v[232:235], v[112:115], v[64:79]
	ds_read_b128 v[228:231], v203 offset:32768
	ds_read_b128 v[232:235], v203 offset:40960
	v_add_f32_e32 v212, v248, v212
	v_add_f32_e32 v212, v249, v212
	v_add_f32_e32 v212, v250, v212
	v_add_f32_e32 v212, v251, v212
	v_add_f32_e32 v212, v221, v212
	v_add_f32_e32 v212, v222, v212
	s_waitcnt lgkmcnt(1)
	v_mfma_f32_32x32x16_bf16 v[80:95], v[228:231], v[108:111], v[80:95]
	v_add_f32_e32 v212, v223, v212
	v_add_f32_e32 v212, v224, v212
	v_add_f32_e32 v212, v225, v212
	v_add_f32_e32 v212, v214, v212
	v_add_f32_e32 v212, v215, v212
	v_add_f32_e32 v212, v216, v212
	s_waitcnt lgkmcnt(0)
	v_mfma_f32_32x32x16_bf16 v[64:79], v[232:235], v[108:111], v[64:79]
	ds_read_b128 v[228:231], v204 offset:32768
	ds_read_b128 v[232:235], v204 offset:40960
	v_add_f32_e32 v212, v217, v212
	v_add_f32_e32 v212, v218, v212
	v_add_f32_e32 v212, v219, v212
	v_add_f32_e32 v212, v220, v212
	v_add_f32_e32 v212, v252, v212
	v_add_f32_e32 v212, v226, v212
	s_waitcnt lgkmcnt(1)
	v_mfma_f32_32x32x16_bf16 v[80:95], v[228:231], v[104:107], v[80:95]
	v_add_f32_e32 v212, v227, v212
	v_add_f32_e32 v212, v253, v212
	v_mov_b32_e32 v213, v212
	v_cvt_pk_bf16_f32 v160, v236, v237
	v_cvt_pk_bf16_f32 v161, v238, v239
	v_cvt_pk_bf16_f32 v162, v240, v241
	s_waitcnt lgkmcnt(0)
	v_mfma_f32_32x32x16_bf16 v[64:79], v[232:235], v[104:107], v[64:79]
	ds_read_b128 v[228:231], v205 offset:32768
	ds_read_b128 v[232:235], v205 offset:40960
	v_cvt_pk_bf16_f32 v163, v242, v243
	v_cvt_pk_bf16_f32 v164, v244, v245
	v_cvt_pk_bf16_f32 v165, v246, v247
	v_cvt_pk_bf16_f32 v166, v248, v249
	v_cvt_pk_bf16_f32 v167, v250, v251
	v_cvt_pk_bf16_f32 v168, v221, v222
	s_waitcnt lgkmcnt(1)
	v_mfma_f32_32x32x16_bf16 v[80:95], v[228:231], v[100:103], v[80:95]
	v_cvt_pk_bf16_f32 v169, v223, v224
	v_cvt_pk_bf16_f32 v170, v225, v214
	v_cvt_pk_bf16_f32 v171, v215, v216
	v_cvt_pk_bf16_f32 v172, v217, v218
	v_cvt_pk_bf16_f32 v173, v219, v220
	v_cvt_pk_bf16_f32 v174, v252, v226
	s_waitcnt lgkmcnt(0)
	v_mfma_f32_32x32x16_bf16 v[64:79], v[232:235], v[100:103], v[64:79]
	ds_read_b128 v[228:231], v206 offset:32768
	ds_read_b128 v[232:235], v206 offset:40960
	v_cvt_pk_bf16_f32 v175, v227, v253
	v_permlane32_swap_b32_e32 v212, v213
	v_permlane32_swap_b32_e32 v160, v162
	v_permlane32_swap_b32_e32 v161, v163
	v_permlane32_swap_b32_e32 v164, v166
	v_permlane32_swap_b32_e32 v165, v167
	s_waitcnt lgkmcnt(1)
	v_mfma_f32_32x32x16_bf16 v[80:95], v[228:231], v[96:99], v[80:95]
	v_permlane32_swap_b32_e32 v168, v170
	v_permlane32_swap_b32_e32 v169, v171
	v_permlane32_swap_b32_e32 v172, v174
	v_permlane32_swap_b32_e32 v173, v175
	s_waitcnt lgkmcnt(0)
	v_mfma_f32_32x32x16_bf16 v[64:79], v[232:235], v[96:99], v[64:79]
	s_cmpk_gt_u32 s61, 0x80
	s_cselect_b64 s[30:31], -1, 0
	s_and_b64 vcc, exec, s[30:31]
	s_cbranch_vccnz .LBB0_2129
	v_add_co_u32_e32 v132, vcc, 0xfffe8000, v184
	s_nop 1
	v_addc_co_u32_e32 v133, vcc, -1, v185, vcc
	global_load_dwordx4 v[128:131], v[132:133], off
	global_load_dwordx4 v[140:143], v[132:133], off offset:-512
	global_load_dwordx4 v[136:139], v[184:185], off
	s_nop 0
	global_load_dwordx4 v[132:135], v[184:185], off offset:-512

; #define SWRITE(b, i) do { *(LAS bf16x8*)(V_lds + (b) * SHM_V + vst0) = sr_[i].vs0;          \
;     *(LAS bf16x8*)(V_lds + (b) * SHM_V + vst1) = sr_[i].vs1; const int kc = sc * 2;               \
;     *(LAS bf16x8*)(K_lds + (b) * SHM_K + KSWZ(sr, kc)) = sr_[i].ks0;                       \
;     *(LAS bf16x8*)(K_lds + (b) * SHM_K + KSWZ(32 + sr, kc)) = sr_[i].ks1; } while (0)
; #define SWAIT() asm volatile("s_waitcnt vmcnt(4)" ::: "memory")
; #define RESC(a) do { if (__any((a) < 1.f)) { if (hi == 0) al_l[r32] = (a); asm volatile("s_waitcnt lgkmcnt(0)" ::: "memory"); \
;     _Pragma("unroll") for (int d = 0; d < NDV; ++d) _Pragma("unroll") for (int r = 0; r < 16; ++r) o[d][r] *= al_l[crow(r, hi)]; } } while (0)
; __device__ __forceinline__ void partialSM(f32x16& p0, f32x16& p1, float& m_reg, float& mn, float& alpha, float C, float thr) {
;     ...
;   if (__builtin_expect(__all(pmax - m_reg <= thr), 1)) { mn = m_reg; alpha = 1.f; }
;   else { mn = fmaxf(m_reg, pmax); alpha = __builtin_amdgcn_exp2f((m_reg - mn) * C); m_reg = mn; }
;   const float mnC = -mn * C;
; #pragma unroll
;   for (int r = 0; r < 16; ++r) p0[r] = fmaf(p0[r], C, mnC);
; #pragma unroll
;   for (int r = 0; r < 16; ++r) p1[r] = fmaf(p1[r], C, mnC);
; #pragma unroll
;   for (int r = 0; r < 16; ++r) p0[r] = __builtin_amdgcn_exp2f(p0[r]);
; template <int NDQ, int NDV> ...
;     ...
;     pv_d0<NDV>(o, vb0 + SHM_V, pa0, pa1, pa2, pa3); partialSM(pA0, pA1, m_reg, mnA, alA, Cs, thr);
;     __syncthreads(); SWAIT(); SWRITE(1, SO);
;     RESC(alA); __syncthreads();
.Lgqa_backB:
	v_cndmask_b32_e64 v234, v234, v211, s[2:3]
	v_mul_f32_e32 v252, 0xbe0293ee, v234
	v_fmamk_f32 v80, v80, 0x3e0293ee, v252
	s_waitcnt lgkmcnt(6)
	v_mfma_f32_32x32x16_bf16 v[48:63], v[164:167], v[218:221], v[48:63]
	ds_read_b64_tr_b16 v[218:219], v193 offset:0x1400
	ds_read_b64_tr_b16 v[220:221], v193 offset:0x1c00
	v_fmamk_f32 v81, v81, 0x3e0293ee, v252
	v_fmamk_f32 v82, v82, 0x3e0293ee, v252
	v_fmamk_f32 v83, v83, 0x3e0293ee, v252
	v_fmamk_f32 v84, v84, 0x3e0293ee, v252
	v_fmamk_f32 v85, v85, 0x3e0293ee, v252
	v_fmamk_f32 v86, v86, 0x3e0293ee, v252
	s_waitcnt lgkmcnt(6)
	v_mfma_f32_32x32x16_bf16 v[48:63], v[168:171], v[222:225], v[48:63]
	ds_read_b64_tr_b16 v[222:223], v193 offset:0x2400
	ds_read_b64_tr_b16 v[224:225], v193 offset:0x2c00
	ds_read_b64_tr_b16 v[226:227], v193 offset:0x3400
	ds_read_b64_tr_b16 v[228:229], v193 offset:0x3c00
	v_fmamk_f32 v87, v87, 0x3e0293ee, v252
	v_fmamk_f32 v88, v88, 0x3e0293ee, v252
	v_fmamk_f32 v89, v89, 0x3e0293ee, v252
	v_fmamk_f32 v90, v90, 0x3e0293ee, v252
	v_fmamk_f32 v91, v91, 0x3e0293ee, v252
	v_fmamk_f32 v92, v92, 0x3e0293ee, v252
	s_waitcnt lgkmcnt(8)
	v_mfma_f32_32x32x16_bf16 v[48:63], v[172:175], v[230:233], v[48:63]
	v_fmamk_f32 v93, v93, 0x3e0293ee, v252
	v_fmamk_f32 v94, v94, 0x3e0293ee, v252
	v_fmamk_f32 v95, v95, 0x3e0293ee, v252
	v_exp_f32_e32 v236, v80
	s_waitcnt lgkmcnt(6)
	v_mfma_f32_32x32x16_bf16 v[32:47], v[160:163], v[214:217], v[32:47]
	ds_read_b64_tr_b16 v[214:215], v193 offset:0x600
	ds_read_b64_tr_b16 v[216:217], v193 offset:0xe00
	v_exp_f32_e32 v237, v81
	v_exp_f32_e32 v238, v82
	v_exp_f32_e32 v239, v83
	s_waitcnt lgkmcnt(6)
	v_mfma_f32_32x32x16_bf16 v[32:47], v[164:167], v[218:221], v[32:47]
	ds_read_b64_tr_b16 v[218:219], v193 offset:0x1600
	ds_read_b64_tr_b16 v[220:221], v193 offset:0x1e00
	v_exp_f32_e32 v240, v84
	v_exp_f32_e32 v241, v85
	v_exp_f32_e32 v242, v86
	s_waitcnt lgkmcnt(6)
	v_mfma_f32_32x32x16_bf16 v[32:47], v[168:171], v[222:225], v[32:47]
	ds_read_b64_tr_b16 v[222:223], v193 offset:0x2600
	ds_read_b64_tr_b16 v[224:225], v193 offset:0x2e00
	ds_read_b64_tr_b16 v[230:231], v193 offset:0x3600
	ds_read_b64_tr_b16 v[232:233], v193 offset:0x3e00
	v_exp_f32_e32 v243, v87
	v_exp_f32_e32 v244, v88
	v_exp_f32_e32 v245, v89
	s_waitcnt lgkmcnt(8)
	v_mfma_f32_32x32x16_bf16 v[32:47], v[172:175], v[226:229], v[32:47]
	v_exp_f32_e32 v246, v90
	v_exp_f32_e32 v247, v91
	v_exp_f32_e32 v248, v92
	s_waitcnt lgkmcnt(6)
	v_mfma_f32_32x32x16_bf16 v[16:31], v[160:163], v[214:217], v[16:31]
	v_exp_f32_e32 v249, v93
	v_exp_f32_e32 v250, v94
	v_exp_f32_e32 v251, v95
	s_waitcnt lgkmcnt(4)
	v_mfma_f32_32x32x16_bf16 v[16:31], v[164:167], v[218:221], v[16:31]
	s_waitcnt lgkmcnt(2)
	v_mfma_f32_32x32x16_bf16 v[16:31], v[168:171], v[222:225], v[16:31]
	s_waitcnt lgkmcnt(0)
	v_mfma_f32_32x32x16_bf16 v[16:31], v[172:175], v[230:233], v[16:31]
	v_cndmask_b32_e64 v161, v253, 1.0, s[2:3]
	v_cmp_gt_f32_e32 vcc, 1.0, v161
	s_barrier
	s_waitcnt vmcnt(4)
	s_cmp_lg_u64 s[30:31], 0
	s_cbranch_scc0 .Lgqa_nodrain
	s_waitcnt vmcnt(0)
.Lgqa_nodrain:
	ds_write_b128 v197, v[144:147] offset:16384
	ds_write_b128 v198, v[156:159] offset:16384
	s_cbranch_vccz .LBB0_2133
	s_and_saveexec_b64 s[36:37], s[0:1]
	ds_write_b32 v191, v161 offset:128
	s_or_b64 exec, exec, s[36:37]
	s_waitcnt lgkmcnt(0)
	v_add_u32_e32 v156, v183, v176
	ds_read_b128 v[144:147], v156 offset:224
	ds_read_b128 v[148:151], v156 offset:192
	ds_read_b128 v[152:155], v156 offset:160
	ds_read_b128 v[156:159], v156 offset:128
	s_waitcnt lgkmcnt(3)
	v_pk_mul_f32 v[12:13], v[12:13], v[144:145]
	s_waitcnt lgkmcnt(2)
	v_pk_mul_f32 v[8:9], v[8:9], v[148:149]
	s_waitcnt lgkmcnt(1)
	v_pk_mul_f32 v[4:5], v[4:5], v[152:153]
	v_pk_mul_f32 v[14:15], v[14:15], v[146:147]
	v_pk_mul_f32 v[10:11], v[10:11], v[150:151]
	v_pk_mul_f32 v[6:7], v[6:7], v[154:155]
	s_waitcnt lgkmcnt(0)
	v_pk_mul_f32 v[2:3], v[2:3], v[158:159]
	v_pk_mul_f32 v[0:1], v[0:1], v[156:157]
	v_pk_mul_f32 v[60:61], v[60:61], v[144:145]
	v_pk_mul_f32 v[56:57], v[56:57], v[148:149]
	v_pk_mul_f32 v[52:53], v[52:53], v[152:153]
	v_pk_mul_f32 v[62:63], v[62:63], v[146:147]
	v_pk_mul_f32 v[58:59], v[58:59], v[150:151]
	v_pk_mul_f32 v[54:55], v[54:55], v[154:155]
	v_pk_mul_f32 v[50:51], v[50:51], v[158:159]
	v_pk_mul_f32 v[48:49], v[48:49], v[156:157]
	v_pk_mul_f32 v[44:45], v[44:45], v[144:145]
	v_pk_mul_f32 v[40:41], v[40:41], v[148:149]
	v_pk_mul_f32 v[36:37], v[36:37], v[152:153]
	v_pk_mul_f32 v[46:47], v[46:47], v[146:147]
	v_pk_mul_f32 v[42:43], v[42:43], v[150:151]
	v_pk_mul_f32 v[38:39], v[38:39], v[154:155]
	v_pk_mul_f32 v[34:35], v[34:35], v[158:159]
	v_pk_mul_f32 v[32:33], v[32:33], v[156:157]
	v_pk_mul_f32 v[28:29], v[28:29], v[144:145]
	v_pk_mul_f32 v[24:25], v[24:25], v[148:149]
	v_pk_mul_f32 v[20:21], v[20:21], v[152:153]
	v_pk_mul_f32 v[30:31], v[30:31], v[146:147]
	v_pk_mul_f32 v[26:27], v[26:27], v[150:151]
	v_pk_mul_f32 v[22:23], v[22:23], v[154:155]
	v_pk_mul_f32 v[18:19], v[18:19], v[158:159]
	v_pk_mul_f32 v[16:17], v[16:17], v[156:157]
